# S5 pass 2: B*u on the f32 matrix core per 32 steps (same fma order), 16 recurrence steps per trip from the tile registers
# speedup vs baseline: 1.0237x; 1.0086x over previous
; __device__ __forceinline__ unsigned pk2(float lo, float hi) { return pg8::cvt_pk_bf16(lo, hi); }
; template <int PASS>
; __device__ __forceinline__ void s5_task(CArgs* Ap, int l, int b, int g, int c, LAS unsigned char* wl, int lane) {
;     ...
;     const float nr = ab_re - 1.f, ni = ab_im, den = a_re * a_re + a_im * a_im;
;     const float f_re = (nr * a_re + ni * a_im) / den, f_im = (ni * a_re - nr * a_im) / den;
;     float bbr[16], bbi[16]; f32x2 bb2[16];
;     {
;         const f32x4* br = (const f32x4*)(Ap->in[9] + ((size_t)(l * NGRP + g) * NST + p) * 16); const f32x4* bi = (const f32x4*)(Ap->in[10] + ((size_t)(l * NGRP + g) * NST + p) * 16);
; #pragma unroll
;         for (int q = 0; q < 4; ++q) { const f32x4 vr = br[q], vi = bi[q];
; #pragma unroll
;             for (int i = 0; i < 4; ++i) { bbr[4 * q + i] = f_re * vr[i] - f_im * vi[i]; bbi[4 * q + i] = f_re * vi[i] + f_im * vr[i]; bb2[4 * q + i] = (f32x2){bbr[4 * q + i], bbi[4 * q + i]}; } }
;     ...
;         const float* cre = Ap->in[11] + ((size_t)(l * NGRP + g) * 16 + n16) * NST; const float* cim = Ap->in[12] + ((size_t)(l * NGRP + g) * 16 + n16) * NST;
; #pragma unroll
;         for (int kk = 0; kk < 4; ++kk) { const f32x4 r4 = *(const f32x4*)(cre + 16 * kk + 4 * g4), i4 = *(const f32x4*)(cim + 16 * kk + 4 * g4);
;             u32x4 w; w.x = pk2(r4[0], -i4[0]); w.y = pk2(r4[1], -i4[1]); w.z = pk2(r4[2], -i4[2]); w.w = pk2(r4[3], -i4[3]);
;             cB[kk] = __builtin_bit_cast(bf16x8, w); }
;         dval = Ap->in[13][l * DSSM + g * 16 + n16];
;     }
;     const size_t row0 = (size_t)b * SEQ + (size_t)c * CHUNK;
;     const bf16_t* up = P + (row0 + (lane >> 2)) * NINP + g * 16 + 4 * (lane & 3);
;     u32x2 unext = *(const u32x2*)up;
.LBB0_878:
	v_add_f32_e32 v48, -1.0, v46
	v_mov_b32_e32 v56, v53
	v_pk_mul_f32 v[54:55], v[52:53], v[52:53]
	v_pk_mul_f32 v[56:57], v[56:57], v[48:49] op_sel:[0,1] op_sel_hi:[0,0]
	v_pk_fma_f32 v[58:59], v[52:53], v[48:49], v[56:57] op_sel_hi:[0,1,1] neg_lo:[0,0,1] neg_hi:[0,0,1]
	v_pk_add_f32 v[54:55], v[54:55], v[54:55] op_sel:[0,1] op_sel_hi:[0,1]
	v_div_scale_f32 v45, s[34:35], v55, v55, v59
	v_rcp_f32_e32 v47, v45
	v_pk_fma_f32 v[52:53], v[52:53], v[48:49], v[56:57]
	s_ashr_i32 s1, s0, 31
	s_ashr_i32 s15, s14, 31
	v_fma_f32 v48, -v45, v47, 1.0
	v_fmac_f32_e32 v47, v48, v47
	v_div_scale_f32 v48, vcc, v59, v55, v59
	v_mul_f32_e32 v53, v48, v47
	v_fma_f32 v56, -v45, v53, v48
	v_fmac_f32_e32 v53, v56, v47
	v_fma_f32 v45, -v45, v53, v48
	v_div_scale_f32 v48, s[34:35], v54, v54, v52
	v_rcp_f32_e32 v56, v48
	v_div_fmas_f32 v45, v45, v47, v53
	v_div_fixup_f32 v83, v45, v55, v59
	s_lshl_b64 s[0:1], s[0:1], 13
	v_fma_f32 v45, -v48, v56, 1.0
	v_fmac_f32_e32 v56, v45, v56
	v_div_scale_f32 v45, vcc, v52, v54, v52
	v_mul_f32_e32 v47, v45, v56
	v_fma_f32 v53, -v48, v47, v45
	v_fmac_f32_e32 v47, v53, v56
	v_fma_f32 v45, -v48, v47, v45
	v_div_fmas_f32 v45, v45, v56, v47
	v_div_fixup_f32 v82, v45, v54, v52
	s_waitcnt vmcnt(0)
	v_pk_mul_f32 v[54:55], v[82:83], v[28:29] op_sel:[1,0] op_sel_hi:[0,0]
	v_pk_fma_f32 v[52:53], v[24:25], v[82:83], v[54:55] neg_lo:[0,0,1] neg_hi:[0,0,1]
	v_pk_fma_f32 v[54:55], v[24:25], v[82:83], v[54:55] op_sel_hi:[0,1,1]
	v_pk_mul_f32 v[28:29], v[82:83], v[28:29] op_sel:[1,1] op_sel_hi:[0,1]
	v_mov_b32_e32 v53, v55
	v_pk_fma_f32 v[54:55], v[24:25], v[82:83], v[28:29] op_sel:[1,0,0] neg_lo:[0,0,1] neg_hi:[0,0,1]
	v_pk_fma_f32 v[24:25], v[24:25], v[82:83], v[28:29] op_sel:[1,0,0]
	s_lshl_b64 s[14:15], s[14:15], 9
	v_mov_b32_e32 v55, v25
	v_pk_mul_f32 v[24:25], v[82:83], v[30:31] op_sel:[1,0] op_sel_hi:[0,0]
	v_pk_fma_f32 v[56:57], v[26:27], v[82:83], v[24:25] neg_lo:[0,0,1] neg_hi:[0,0,1]
	v_pk_fma_f32 v[24:25], v[26:27], v[82:83], v[24:25] op_sel_hi:[0,1,1]
	v_mov_b32_e32 v24, v31
	v_mov_b32_e32 v57, v25
	v_pk_mul_f32 v[24:25], v[82:83], v[24:25] op_sel:[1,0] op_sel_hi:[0,0]
	v_mov_b32_e32 v26, v27
	v_pk_fma_f32 v[58:59], v[26:27], v[82:83], v[24:25] op_sel_hi:[0,1,1] neg_lo:[0,0,1] neg_hi:[0,0,1]
	v_pk_fma_f32 v[24:25], v[26:27], v[82:83], v[24:25] op_sel_hi:[0,1,1]
	v_mov_b32_e32 v59, v25
	v_pk_mul_f32 v[24:25], v[82:83], v[20:21] op_sel:[1,0] op_sel_hi:[0,0]
	v_pk_fma_f32 v[60:61], v[82:83], v[16:17], v[24:25] neg_lo:[0,0,1] neg_hi:[0,0,1]
	v_pk_fma_f32 v[24:25], v[82:83], v[16:17], v[24:25] op_sel_hi:[1,0,1]
	v_mov_b32_e32 v16, v21
	v_mov_b32_e32 v21, s17
	v_or_b32_e32 v20, s16, v32
	v_pk_mul_f32 v[62:63], v[82:83], v[16:17] op_sel:[1,0] op_sel_hi:[0,0]
	v_mov_b32_e32 v16, v17
	v_lshlrev_b64 v[20:21], 2, v[20:21]
	v_lshl_add_u64 v[64:65], v[36:37], 0, v[20:21]
	v_lshl_add_u64 v[66:67], v[38:39], 0, v[20:21]
	v_pk_fma_f32 v[20:21], v[82:83], v[16:17], v[62:63] op_sel_hi:[1,0,1] neg_lo:[0,0,1] neg_hi:[0,0,1]
	v_pk_fma_f32 v[16:17], v[82:83], v[16:17], v[62:63] op_sel_hi:[1,0,1]
	s_add_u32 s0, s14, s0
	v_mov_b32_e32 v21, v17
	v_pk_mul_f32 v[16:17], v[82:83], v[22:23] op_sel:[1,0] op_sel_hi:[0,0]
	v_pk_fma_f32 v[62:63], v[82:83], v[18:19], v[16:17] neg_lo:[0,0,1] neg_hi:[0,0,1]
	v_pk_fma_f32 v[16:17], v[82:83], v[18:19], v[16:17] op_sel_hi:[1,0,1]
	v_mov_b32_e32 v18, v19
	v_mov_b32_e32 v16, v23
	v_pk_mul_f32 v[68:69], v[82:83], v[16:17] op_sel:[1,0] op_sel_hi:[0,0]
	v_mov_b32_e32 v63, v17
	v_pk_fma_f32 v[22:23], v[82:83], v[18:19], v[68:69] op_sel_hi:[1,0,1] neg_lo:[0,0,1] neg_hi:[0,0,1]
	v_or_b32_e32 v19, s0, v34
	v_mov_b64_e32 v[16:17], s[20:21]
	s_addc_u32 s1, s15, s1
	v_mad_u64_u32 v[16:17], s[14:15], v19, s79, v[16:17]
	v_mad_i32_i24 v17, s1, v180, v17
	s_lshl_b32 s72, s31, 5
	v_mov_b32_e32 v61, v25
	s_mul_i32 s36, s0, s79
	v_and_b32_e32 v126, 31, v89
	s_add_u32 s36, s36, s20
	s_addc_u32 s37, s21, 0
	v_mul_u32_u24_e32 v126, 0x1e00, v126
	s_add_u32 s36, s36, s72
	s_addc_u32 s37, s37, 0
	v_bfe_u32 v127, v89, 5, 1
	global_load_dwordx4 v[244:247], v126, s[36:37]
	global_load_dwordx4 v[248:251], v126, s[36:37] offset:16
	v_lshlrev_b32_e32 v127, 4, v127
	v_sub_u32_e32 v127, 16, v127
	global_load_dwordx4 v[28:31], v[66:67], off
	global_load_dwordx4 v[24:27], v[64:65], off
	global_load_dwordx4 v[98:101], v[66:67], off offset:64
	global_load_dwordx4 v[102:105], v[64:65], off offset:64
	global_load_dwordx4 v[106:109], v[66:67], off offset:128
	global_load_dwordx4 v[110:113], v[64:65], off offset:128
	global_load_dwordx4 v[114:117], v[64:65], off offset:192
; __device__ __forceinline__ unsigned pk2(float lo, float hi) { return pg8::cvt_pk_bf16(lo, hi); }
; template <int PASS>
; __device__ __forceinline__ void s5_task(CArgs* Ap, int l, int b, int g, int c, LAS unsigned char* wl, int lane) {
;     ...
;         for (int q = 0; q < 4; ++q) { const f32x4 vr = br[q], vi = bi[q];
; #pragma unroll
;             for (int i = 0; i < 4; ++i) { bbr[4 * q + i] = f_re * vr[i] - f_im * vi[i]; bbi[4 * q + i] = f_re * vi[i] + f_im * vr[i]; bb2[4 * q + i] = (f32x2){bbr[4 * q + i], bbi[4 * q + i]}; } }
;     ...
;         const float* cre = Ap->in[11] + ((size_t)(l * NGRP + g) * 16 + n16) * NST; const float* cim = Ap->in[12] + ((size_t)(l * NGRP + g) * 16 + n16) * NST;
; #pragma unroll
;         for (int kk = 0; kk < 4; ++kk) { const f32x4 r4 = *(const f32x4*)(cre + 16 * kk + 4 * g4), i4 = *(const f32x4*)(cim + 16 * kk + 4 * g4);
;             u32x4 w; w.x = pk2(r4[0], -i4[0]); w.y = pk2(r4[1], -i4[1]); w.z = pk2(r4[2], -i4[2]); w.w = pk2(r4[3], -i4[3]);
;             cB[kk] = __builtin_bit_cast(bf16x8, w); }
;         dval = Ap->in[13][l * DSSM + g * 16 + n16];
;     }
;     const size_t row0 = (size_t)b * SEQ + (size_t)c * CHUNK;
;     const bf16_t* up = P + (row0 + (lane >> 2)) * NINP + g * 16 + 4 * (lane & 3);
;     u32x2 unext = *(const u32x2*)up;
	global_load_dwordx4 v[118:121], v[66:67], off offset:192
	v_lshl_add_u64 v[16:17], v[16:17], 0, s[72:73]
	v_mov_b32_e32 v45, v145
	v_lshl_or_b32 v144, s31, 4, v85
	v_lshl_add_u64 v[64:65], v[16:17], 0, v[44:45]
	v_lshl_add_u64 v[66:67], v[144:145], 2, s[18:19]
	global_load_dwordx2 v[16:17], v[64:65], off
	global_load_dword v45, v[66:67], off
	v_pk_fma_f32 v[18:19], v[82:83], v[18:19], v[68:69] op_sel_hi:[1,0,1]
	v_xor_b32_e32 v48, 0x80000000, v49
	v_mov_b32_e32 v23, v19
	v_pk_mul_f32 v[18:19], v[82:83], v[12:13] op_sel:[1,0] op_sel_hi:[0,0]
	v_pk_fma_f32 v[66:67], v[82:83], v[8:9], v[18:19] neg_lo:[0,0,1] neg_hi:[0,0,1]
	v_pk_fma_f32 v[18:19], v[82:83], v[8:9], v[18:19] op_sel_hi:[1,0,1]
	v_mov_b32_e32 v8, v13
	v_pk_mul_f32 v[12:13], v[82:83], v[8:9] op_sel:[1,0] op_sel_hi:[0,0]
	v_mov_b32_e32 v8, v9
	v_pk_fma_f32 v[68:69], v[82:83], v[8:9], v[12:13] op_sel_hi:[1,0,1] neg_lo:[0,0,1] neg_hi:[0,0,1]
	v_pk_fma_f32 v[8:9], v[82:83], v[8:9], v[12:13] op_sel_hi:[1,0,1]
	v_mov_b32_e32 v67, v19
	v_mov_b32_e32 v69, v9
	v_pk_mul_f32 v[8:9], v[82:83], v[14:15] op_sel:[1,0] op_sel_hi:[0,0]
	v_pk_fma_f32 v[70:71], v[82:83], v[10:11], v[8:9] neg_lo:[0,0,1] neg_hi:[0,0,1]
	v_pk_fma_f32 v[8:9], v[82:83], v[10:11], v[8:9] op_sel_hi:[1,0,1]
	v_mov_b32_e32 v10, v11
	v_mov_b32_e32 v8, v15
	v_mov_b32_e32 v71, v9
	v_pk_mul_f32 v[8:9], v[82:83], v[8:9] op_sel:[1,0] op_sel_hi:[0,0]
	v_pk_fma_f32 v[72:73], v[82:83], v[10:11], v[8:9] op_sel_hi:[1,0,1] neg_lo:[0,0,1] neg_hi:[0,0,1]
	v_pk_fma_f32 v[8:9], v[82:83], v[10:11], v[8:9] op_sel_hi:[1,0,1]
	v_mov_b32_e32 v47, v46
	v_mov_b32_e32 v73, v9
	v_pk_mul_f32 v[8:9], v[82:83], v[4:5] op_sel:[1,0] op_sel_hi:[0,0]
	v_pk_fma_f32 v[74:75], v[82:83], v[0:1], v[8:9] neg_lo:[0,0,1] neg_hi:[0,0,1]
	v_pk_fma_f32 v[8:9], v[82:83], v[0:1], v[8:9] op_sel_hi:[1,0,1]
	v_mov_b32_e32 v0, v5
	v_pk_mul_f32 v[4:5], v[82:83], v[0:1] op_sel:[1,0] op_sel_hi:[0,0]
	v_mov_b32_e32 v0, v1
	v_pk_fma_f32 v[76:77], v[82:83], v[0:1], v[4:5] op_sel_hi:[1,0,1] neg_lo:[0,0,1] neg_hi:[0,0,1]
	v_pk_fma_f32 v[0:1], v[82:83], v[0:1], v[4:5] op_sel_hi:[1,0,1]
	v_mov_b32_e32 v75, v9
	v_mov_b32_e32 v77, v1
	v_pk_mul_f32 v[0:1], v[82:83], v[6:7] op_sel:[1,0] op_sel_hi:[0,0]
	v_pk_fma_f32 v[78:79], v[82:83], v[2:3], v[0:1] neg_lo:[0,0,1] neg_hi:[0,0,1]
	v_pk_fma_f32 v[0:1], v[82:83], v[2:3], v[0:1] op_sel_hi:[1,0,1]
	v_mov_b32_e32 v2, v7
	v_mov_b32_e32 v0, v3
	v_pk_mul_f32 v[2:3], v[82:83], v[2:3] op_sel:[1,0] op_sel_hi:[0,0]
	v_mov_b32_e32 v79, v1
	v_pk_fma_f32 v[80:81], v[82:83], v[0:1], v[2:3] op_sel_hi:[1,0,1] neg_lo:[0,0,1] neg_hi:[0,0,1]
	v_pk_fma_f32 v[0:1], v[82:83], v[0:1], v[2:3] op_sel_hi:[1,0,1]
	s_mov_b32 s16, 0
	v_mov_b32_e32 v81, v1
	s_waitcnt vmcnt(9)
	v_xor_b32_e32 v0, 0x80000000, v28
	v_xor_b32_e32 v1, 0x80000000, v29
	v_xor_b32_e32 v2, 0x80000000, v30
	v_xor_b32_e32 v3, 0x80000000, v31
	s_waitcnt vmcnt(7)
	v_xor_b32_e32 v4, 0x80000000, v98
	v_xor_b32_e32 v5, 0x80000000, v99
	v_xor_b32_e32 v6, 0x80000000, v100
	v_xor_b32_e32 v7, 0x80000000, v101
	s_waitcnt vmcnt(5)
	v_xor_b32_e32 v8, 0x80000000, v106
	v_xor_b32_e32 v9, 0x80000000, v107
	v_xor_b32_e32 v10, 0x80000000, v108
	v_xor_b32_e32 v11, 0x80000000, v109
	s_waitcnt vmcnt(2)
	v_xor_b32_e32 v12, 0x80000000, v118
	v_xor_b32_e32 v13, 0x80000000, v119
	v_xor_b32_e32 v14, 0x80000000, v120
	v_xor_b32_e32 v15, 0x80000000, v121
	v_cvt_pk_bf16_f32 v0, v24, v0
	v_cvt_pk_bf16_f32 v1, v25, v1
	v_cvt_pk_bf16_f32 v2, v26, v2
	v_cvt_pk_bf16_f32 v3, v27, v3
	v_cvt_pk_bf16_f32 v4, v102, v4
	v_cvt_pk_bf16_f32 v5, v103, v5
	v_cvt_pk_bf16_f32 v6, v104, v6
	v_cvt_pk_bf16_f32 v7, v105, v7
	v_cvt_pk_bf16_f32 v8, v110, v8
	v_cvt_pk_bf16_f32 v9, v111, v9
	v_cvt_pk_bf16_f32 v10, v112, v10
	v_cvt_pk_bf16_f32 v11, v113, v11
	v_cvt_pk_bf16_f32 v12, v114, v12
	v_cvt_pk_bf16_f32 v13, v115, v13
	v_cvt_pk_bf16_f32 v14, v116, v14
	v_cvt_pk_bf16_f32 v15, v117, v15
	v_lshl_add_u64 v[24:25], v[40:41], 0, s[72:73]
	s_waitcnt vmcnt(1)
	v_mov_b64_e32 v[26:27], v[16:17]
	s_nop 1
	v_permlane32_swap_b32_e32 v52, v54
	v_permlane32_swap_b32_e32 v53, v55
	v_permlane32_swap_b32_e32 v56, v58
	v_permlane32_swap_b32_e32 v57, v59
	v_permlane32_swap_b32_e32 v60, v20
	v_permlane32_swap_b32_e32 v61, v21
	v_permlane32_swap_b32_e32 v62, v22
	v_permlane32_swap_b32_e32 v63, v23
	v_permlane32_swap_b32_e32 v66, v68
	v_permlane32_swap_b32_e32 v67, v69
	v_permlane32_swap_b32_e32 v70, v72
	v_permlane32_swap_b32_e32 v71, v73
	v_permlane32_swap_b32_e32 v74, v76
	v_permlane32_swap_b32_e32 v75, v77
	v_permlane32_swap_b32_e32 v78, v80
	v_permlane32_swap_b32_e32 v79, v81

; #define LAS __attribute__((address_space(3)))
; __device__ __forceinline__ unsigned pk2(float lo, float hi) { return pg8::cvt_pk_bf16(lo, hi); }
; __device__ __forceinline__ float bflo(unsigned w) { return __uint_as_float(w << 16); }
; __device__ __forceinline__ float bfhi(unsigned w) { return __uint_as_float(w & 0xffff0000u); }
; __device__ __forceinline__ void wave_lds_fence() { asm volatile("s_waitcnt lgkmcnt(0)" ::: "memory"); }
; template <int PASS>
; __device__ __forceinline__ void s5_task(CArgs* Ap, int l, int b, int g, int c, LAS unsigned char* wl, int lane) {
;     ...
;     for (int tb = 0; tb < CHUNK; tb += 16) {
;         const u32x2 ucur = unext;
;         if (tb + 16 < CHUNK) unext = *(const u32x2*)(up + (size_t)(tb + 16) * NINP);
;         *(LAS f32x4*)(us + (lane >> 2) * 16 + 4 * (lane & 3)) = (f32x4){bflo(ucur.x), bfhi(ucur.x), bflo(ucur.y), bfhi(ucur.y)};
;         wave_lds_fence();
; #pragma unroll 4
;         for (int s = 0; s < 16; ++s) {
;             const f32x4 u0 = *(const LAS f32x4*)(us + s * 16), u1 = *(const LAS f32x4*)(us + s * 16 + 4), u2 = *(const LAS f32x4*)(us + s * 16 + 8), u3 = *(const LAS f32x4*)(us + s * 16 + 12);
;             f32x2 bu = (f32x2){0.f, 0.f};
; #pragma unroll
;             for (int i = 0; i < 4; ++i) bu = bb2[i] * (f32x2){u0[i], u0[i]} + bu;
; #pragma unroll
;             for (int i = 0; i < 4; ++i) bu = bb2[4 + i] * (f32x2){u1[i], u1[i]} + bu;
; #pragma unroll
;             for (int i = 0; i < 4; ++i) bu = bb2[8 + i] * (f32x2){u2[i], u2[i]} + bu;
; #pragma unroll
;             for (int i = 0; i < 4; ++i) bu = bb2[12 + i] * (f32x2){u3[i], u3[i]} + bu;
;             const float br_ = bu.x, bi_ = bu.y;
;             const float nxr = fmaf(ab_re, xr, fmaf(-ab_im, xi, br_)); const float nxi = fmaf(ab_re, xi, fmaf(ab_im, xr, bi_));
;             xr = nxr; xi = nxi;
;             if (PASS == 2) *(LAS unsigned*)(Xs + s * 136 + 2 * p) = pk2(xr, xi);
.LBB0_882:
	v_add_u32_e32 v17, s25, v87
	s_and_b32 s31, s16, 16
	s_cmp_eq_u32 s31, 0
	s_cbranch_scc0 .Ls52m_h1
	v_lshlrev_b32_e32 v118, v127, v244
	v_lshlrev_b32_e32 v119, v127, v245
	v_lshlrev_b32_e32 v120, v127, v246
	v_lshlrev_b32_e32 v121, v127, v247
	v_lshlrev_b32_e32 v122, v127, v248
	v_lshlrev_b32_e32 v123, v127, v249
	v_lshlrev_b32_e32 v124, v127, v250
	v_lshlrev_b32_e32 v125, v127, v251
	v_and_b32_e32 v118, 0xffff0000, v118
	v_and_b32_e32 v119, 0xffff0000, v119
	v_and_b32_e32 v120, 0xffff0000, v120
	v_and_b32_e32 v121, 0xffff0000, v121
	v_and_b32_e32 v122, 0xffff0000, v122
	v_and_b32_e32 v123, 0xffff0000, v123
	v_and_b32_e32 v124, 0xffff0000, v124
	v_and_b32_e32 v125, 0xffff0000, v125
	s_cmpk_lt_u32 s16, 0x1e0
	s_cbranch_scc0 .Ls52m_nopf
	s_add_u32 s36, s36, 0x3c000
	s_addc_u32 s37, s37, 0
	global_load_dwordx4 v[244:247], v126, s[36:37]
	global_load_dwordx4 v[248:251], v126, s[36:37] offset:16
.Ls52m_nopf:
	v_mfma_f32_32x32x2_f32 v[102:117], v118, v52, 0
	v_mfma_f32_32x32x2_f32 v[150:165], v118, v54, 0
	v_mfma_f32_32x32x2_f32 v[102:117], v119, v56, v[102:117]
	v_mfma_f32_32x32x2_f32 v[150:165], v119, v58, v[150:165]
	v_mfma_f32_32x32x2_f32 v[102:117], v120, v60, v[102:117]
	v_mfma_f32_32x32x2_f32 v[150:165], v120, v20, v[150:165]
	v_mfma_f32_32x32x2_f32 v[102:117], v121, v62, v[102:117]
	v_mfma_f32_32x32x2_f32 v[150:165], v121, v22, v[150:165]
	v_mfma_f32_32x32x2_f32 v[102:117], v122, v66, v[102:117]
	v_mfma_f32_32x32x2_f32 v[150:165], v122, v68, v[150:165]
	v_mfma_f32_32x32x2_f32 v[102:117], v123, v70, v[102:117]
	v_mfma_f32_32x32x2_f32 v[150:165], v123, v72, v[150:165]
	v_mfma_f32_32x32x2_f32 v[102:117], v124, v74, v[102:117]
	v_mfma_f32_32x32x2_f32 v[150:165], v124, v76, v[150:165]
	v_mfma_f32_32x32x2_f32 v[102:117], v125, v78, v[102:117]
	v_mfma_f32_32x32x2_f32 v[150:165], v125, v80, v[150:165]
	v_mfma_f32_32x32x2_f32 v[184:199], v118, v53, 0
	v_mfma_f32_32x32x2_f32 v[228:243], v118, v55, 0
	v_mfma_f32_32x32x2_f32 v[184:199], v119, v57, v[184:199]
	v_mfma_f32_32x32x2_f32 v[228:243], v119, v59, v[228:243]
	v_mfma_f32_32x32x2_f32 v[184:199], v120, v61, v[184:199]
	v_mfma_f32_32x32x2_f32 v[228:243], v120, v21, v[228:243]
	v_mfma_f32_32x32x2_f32 v[184:199], v121, v63, v[184:199]
	v_mfma_f32_32x32x2_f32 v[228:243], v121, v23, v[228:243]
	v_mfma_f32_32x32x2_f32 v[184:199], v122, v67, v[184:199]
	v_mfma_f32_32x32x2_f32 v[228:243], v122, v69, v[228:243]
	v_mfma_f32_32x32x2_f32 v[184:199], v123, v71, v[184:199]
	v_mfma_f32_32x32x2_f32 v[228:243], v123, v73, v[228:243]
	v_mfma_f32_32x32x2_f32 v[184:199], v124, v75, v[184:199]
	v_mfma_f32_32x32x2_f32 v[228:243], v124, v77, v[228:243]
	v_mfma_f32_32x32x2_f32 v[184:199], v125, v79, v[184:199]
	v_mfma_f32_32x32x2_f32 v[228:243], v125, v81, v[228:243]
	s_nop 1
	v_permlane32_swap_b32_e32 v102, v150
	v_permlane32_swap_b32_e32 v103, v151
	v_permlane32_swap_b32_e32 v104, v152
	v_permlane32_swap_b32_e32 v105, v153
	v_permlane32_swap_b32_e32 v106, v154
	v_permlane32_swap_b32_e32 v107, v155
	v_permlane32_swap_b32_e32 v108, v156
	v_permlane32_swap_b32_e32 v109, v157
	v_permlane32_swap_b32_e32 v110, v158
	v_permlane32_swap_b32_e32 v111, v159
	v_permlane32_swap_b32_e32 v112, v160
	v_permlane32_swap_b32_e32 v113, v161
	v_permlane32_swap_b32_e32 v114, v162
	v_permlane32_swap_b32_e32 v115, v163
	v_permlane32_swap_b32_e32 v116, v164
	v_permlane32_swap_b32_e32 v117, v165
	s_nop 1
	v_permlane32_swap_b32_e32 v184, v228
	v_permlane32_swap_b32_e32 v185, v229
	v_permlane32_swap_b32_e32 v186, v230
	v_permlane32_swap_b32_e32 v187, v231
	v_permlane32_swap_b32_e32 v188, v232
	v_permlane32_swap_b32_e32 v189, v233
	v_permlane32_swap_b32_e32 v190, v234
	v_permlane32_swap_b32_e32 v191, v235
	v_permlane32_swap_b32_e32 v192, v236
	v_permlane32_swap_b32_e32 v193, v237
	v_permlane32_swap_b32_e32 v194, v238
	v_permlane32_swap_b32_e32 v195, v239
	v_permlane32_swap_b32_e32 v196, v240
	v_permlane32_swap_b32_e32 v197, v241
	v_permlane32_swap_b32_e32 v198, v242
	v_permlane32_swap_b32_e32 v199, v243
	v_fmac_f32_e32 v102, v48, v51
	v_fmac_f32_e32 v184, v49, v50
	v_fmac_f32_e32 v102, v46, v50
	v_fmac_f32_e32 v184, v46, v51
	v_cvt_pk_bf16_f32 v118, v102, v184
	ds_write_b32 v17, v118
	v_fmac_f32_e32 v103, v48, v184
	v_fmac_f32_e32 v185, v49, v102
	v_fmac_f32_e32 v103, v46, v102
	v_fmac_f32_e32 v185, v46, v184
	v_cvt_pk_bf16_f32 v119, v103, v185
	ds_write_b32 v17, v119 offset:272
	v_fmac_f32_e32 v104, v48, v185
	v_fmac_f32_e32 v186, v49, v103
	v_fmac_f32_e32 v104, v46, v103
	v_fmac_f32_e32 v186, v46, v185
	v_cvt_pk_bf16_f32 v118, v104, v186
	ds_write_b32 v17, v118 offset:544
	v_fmac_f32_e32 v105, v48, v186
	v_fmac_f32_e32 v187, v49, v104
	v_fmac_f32_e32 v105, v46, v104
	v_fmac_f32_e32 v187, v46, v186
	v_cvt_pk_bf16_f32 v119, v105, v187
	ds_write_b32 v17, v119 offset:816
	v_fmac_f32_e32 v150, v48, v187
	v_fmac_f32_e32 v228, v49, v105
	v_fmac_f32_e32 v150, v46, v105
	v_fmac_f32_e32 v228, v46, v187
	v_cvt_pk_bf16_f32 v118, v150, v228
	ds_write_b32 v17, v118 offset:1088
	v_fmac_f32_e32 v151, v48, v228
	v_fmac_f32_e32 v229, v49, v150
	v_fmac_f32_e32 v151, v46, v150
	v_fmac_f32_e32 v229, v46, v228
	v_cvt_pk_bf16_f32 v119, v151, v229
	ds_write_b32 v17, v119 offset:1360
	v_fmac_f32_e32 v152, v48, v229
	v_fmac_f32_e32 v230, v49, v151
	v_fmac_f32_e32 v152, v46, v151
	v_fmac_f32_e32 v230, v46, v229
	v_cvt_pk_bf16_f32 v118, v152, v230
	ds_write_b32 v17, v118 offset:1632
	v_fmac_f32_e32 v153, v48, v230
	v_fmac_f32_e32 v231, v49, v152
	v_fmac_f32_e32 v153, v46, v152
	v_fmac_f32_e32 v231, v46, v230
	v_cvt_pk_bf16_f32 v119, v153, v231
	ds_write_b32 v17, v119 offset:1904
	v_fmac_f32_e32 v106, v48, v231
	v_fmac_f32_e32 v188, v49, v153
; #define LAS __attribute__((address_space(3)))
; __device__ __forceinline__ unsigned pk2(float lo, float hi) { return pg8::cvt_pk_bf16(lo, hi); }
; template <int PASS>
; __device__ __forceinline__ void s5_task(CArgs* Ap, int l, int b, int g, int c, LAS unsigned char* wl, int lane) {
;     ...
;         for (int s = 0; s < 16; ++s) {
;             const f32x4 u0 = *(const LAS f32x4*)(us + s * 16), u1 = *(const LAS f32x4*)(us + s * 16 + 4), u2 = *(const LAS f32x4*)(us + s * 16 + 8), u3 = *(const LAS f32x4*)(us + s * 16 + 12);
;             f32x2 bu = (f32x2){0.f, 0.f};
; #pragma unroll
;             for (int i = 0; i < 4; ++i) bu = bb2[i] * (f32x2){u0[i], u0[i]} + bu;
; #pragma unroll
;             for (int i = 0; i < 4; ++i) bu = bb2[4 + i] * (f32x2){u1[i], u1[i]} + bu;
; #pragma unroll
;             for (int i = 0; i < 4; ++i) bu = bb2[8 + i] * (f32x2){u2[i], u2[i]} + bu;
; #pragma unroll
;             for (int i = 0; i < 4; ++i) bu = bb2[12 + i] * (f32x2){u3[i], u3[i]} + bu;
;             const float br_ = bu.x, bi_ = bu.y;
;             const float nxr = fmaf(ab_re, xr, fmaf(-ab_im, xi, br_)); const float nxi = fmaf(ab_re, xi, fmaf(ab_im, xr, bi_));
;             xr = nxr; xi = nxi;
;             if (PASS == 2) *(LAS unsigned*)(Xs + s * 136 + 2 * p) = pk2(xr, xi);
	v_fmac_f32_e32 v106, v46, v153
	v_fmac_f32_e32 v188, v46, v231
	v_cvt_pk_bf16_f32 v118, v106, v188
	ds_write_b32 v17, v118 offset:2176
	v_fmac_f32_e32 v107, v48, v188
	v_fmac_f32_e32 v189, v49, v106
	v_fmac_f32_e32 v107, v46, v106
	v_fmac_f32_e32 v189, v46, v188
	v_cvt_pk_bf16_f32 v119, v107, v189
	ds_write_b32 v17, v119 offset:2448
	v_fmac_f32_e32 v108, v48, v189
	v_fmac_f32_e32 v190, v49, v107
	v_fmac_f32_e32 v108, v46, v107
	v_fmac_f32_e32 v190, v46, v189
	v_cvt_pk_bf16_f32 v118, v108, v190
	ds_write_b32 v17, v118 offset:2720
	v_fmac_f32_e32 v109, v48, v190
	v_fmac_f32_e32 v191, v49, v108
	v_fmac_f32_e32 v109, v46, v108
	v_fmac_f32_e32 v191, v46, v190
	v_cvt_pk_bf16_f32 v119, v109, v191
	ds_write_b32 v17, v119 offset:2992
	v_fmac_f32_e32 v154, v48, v191
	v_fmac_f32_e32 v232, v49, v109
	v_fmac_f32_e32 v154, v46, v109
	v_fmac_f32_e32 v232, v46, v191
	v_cvt_pk_bf16_f32 v118, v154, v232
	ds_write_b32 v17, v118 offset:3264
	v_fmac_f32_e32 v155, v48, v232
	v_fmac_f32_e32 v233, v49, v154
	v_fmac_f32_e32 v155, v46, v154
	v_fmac_f32_e32 v233, v46, v232
	v_cvt_pk_bf16_f32 v119, v155, v233
	ds_write_b32 v17, v119 offset:3536
	v_fmac_f32_e32 v156, v48, v233
	v_fmac_f32_e32 v234, v49, v155
	v_fmac_f32_e32 v156, v46, v155
	v_fmac_f32_e32 v234, v46, v233
	v_cvt_pk_bf16_f32 v118, v156, v234
	ds_write_b32 v17, v118 offset:3808
	v_fmac_f32_e32 v157, v48, v234
	v_fmac_f32_e32 v235, v49, v156
	v_fmac_f32_e32 v157, v46, v156
	v_fmac_f32_e32 v235, v46, v234
	v_cvt_pk_bf16_f32 v119, v157, v235
	ds_write_b32 v17, v119 offset:4080
	v_mov_b32_e32 v50, v157
	v_mov_b32_e32 v51, v235
	s_branch .Ls52m_done
.Ls52m_h1:
	v_fmac_f32_e32 v110, v48, v51
	v_fmac_f32_e32 v192, v49, v50
	v_fmac_f32_e32 v110, v46, v50
	v_fmac_f32_e32 v192, v46, v51
	v_cvt_pk_bf16_f32 v118, v110, v192
	ds_write_b32 v17, v118
	v_fmac_f32_e32 v111, v48, v192
	v_fmac_f32_e32 v193, v49, v110
	v_fmac_f32_e32 v111, v46, v110
	v_fmac_f32_e32 v193, v46, v192
	v_cvt_pk_bf16_f32 v119, v111, v193
	ds_write_b32 v17, v119 offset:272
	v_fmac_f32_e32 v112, v48, v193
	v_fmac_f32_e32 v194, v49, v111
	v_fmac_f32_e32 v112, v46, v111
	v_fmac_f32_e32 v194, v46, v193
	v_cvt_pk_bf16_f32 v118, v112, v194
	ds_write_b32 v17, v118 offset:544
	v_fmac_f32_e32 v113, v48, v194
	v_fmac_f32_e32 v195, v49, v112
	v_fmac_f32_e32 v113, v46, v112
	v_fmac_f32_e32 v195, v46, v194
	v_cvt_pk_bf16_f32 v119, v113, v195
	ds_write_b32 v17, v119 offset:816
	v_fmac_f32_e32 v158, v48, v195
	v_fmac_f32_e32 v236, v49, v113
	v_fmac_f32_e32 v158, v46, v113
	v_fmac_f32_e32 v236, v46, v195
	v_cvt_pk_bf16_f32 v118, v158, v236
	ds_write_b32 v17, v118 offset:1088
	v_fmac_f32_e32 v159, v48, v236
	v_fmac_f32_e32 v237, v49, v158
	v_fmac_f32_e32 v159, v46, v158
	v_fmac_f32_e32 v237, v46, v236
	v_cvt_pk_bf16_f32 v119, v159, v237
	ds_write_b32 v17, v119 offset:1360
	v_fmac_f32_e32 v160, v48, v237
	v_fmac_f32_e32 v238, v49, v159
	v_fmac_f32_e32 v160, v46, v159
	v_fmac_f32_e32 v238, v46, v237
	v_cvt_pk_bf16_f32 v118, v160, v238
	ds_write_b32 v17, v118 offset:1632
	v_fmac_f32_e32 v161, v48, v238
	v_fmac_f32_e32 v239, v49, v160
	v_fmac_f32_e32 v161, v46, v160
	v_fmac_f32_e32 v239, v46, v238
	v_cvt_pk_bf16_f32 v119, v161, v239
	ds_write_b32 v17, v119 offset:1904
	v_fmac_f32_e32 v114, v48, v239
	v_fmac_f32_e32 v196, v49, v161
	v_fmac_f32_e32 v114, v46, v161
	v_fmac_f32_e32 v196, v46, v239
	v_cvt_pk_bf16_f32 v118, v114, v196
	ds_write_b32 v17, v118 offset:2176
	v_fmac_f32_e32 v115, v48, v196
	v_fmac_f32_e32 v197, v49, v114
	v_fmac_f32_e32 v115, v46, v114
	v_fmac_f32_e32 v197, v46, v196
	v_cvt_pk_bf16_f32 v119, v115, v197
	ds_write_b32 v17, v119 offset:2448
	v_fmac_f32_e32 v116, v48, v197
	v_fmac_f32_e32 v198, v49, v115
	v_fmac_f32_e32 v116, v46, v115
	v_fmac_f32_e32 v198, v46, v197
	v_cvt_pk_bf16_f32 v118, v116, v198
	ds_write_b32 v17, v118 offset:2720
	v_fmac_f32_e32 v117, v48, v198
	v_fmac_f32_e32 v199, v49, v116
	v_fmac_f32_e32 v117, v46, v116
	v_fmac_f32_e32 v199, v46, v198
	v_cvt_pk_bf16_f32 v119, v117, v199
	ds_write_b32 v17, v119 offset:2992
	v_fmac_f32_e32 v162, v48, v199
	v_fmac_f32_e32 v240, v49, v117
	v_fmac_f32_e32 v162, v46, v117
	v_fmac_f32_e32 v240, v46, v199
	v_cvt_pk_bf16_f32 v118, v162, v240
	ds_write_b32 v17, v118 offset:3264
	v_fmac_f32_e32 v163, v48, v240
	v_fmac_f32_e32 v241, v49, v162
	v_fmac_f32_e32 v163, v46, v162
	v_fmac_f32_e32 v241, v46, v240
	v_cvt_pk_bf16_f32 v119, v163, v241
	ds_write_b32 v17, v119 offset:3536
	v_fmac_f32_e32 v164, v48, v241
	v_fmac_f32_e32 v242, v49, v163
	v_fmac_f32_e32 v164, v46, v163
	v_fmac_f32_e32 v242, v46, v241
	v_cvt_pk_bf16_f32 v118, v164, v242
	ds_write_b32 v17, v118 offset:3808
	v_fmac_f32_e32 v165, v48, v242
	v_fmac_f32_e32 v243, v49, v164
	v_fmac_f32_e32 v165, v46, v164
	v_fmac_f32_e32 v243, v46, v242
	v_cvt_pk_bf16_f32 v119, v165, v243
	ds_write_b32 v17, v119 offset:4080
	v_mov_b32_e32 v50, v165
	v_mov_b32_e32 v51, v243
; #define LAS __attribute__((address_space(3)))
; __device__ __forceinline__ bf16_t f2bf(float f) { return (bf16_t)(pk2(f, f) & 0xffffu); }
; __device__ __forceinline__ float gelu_tanh(float x) { const float z = 0.7978845608f * (x + 0.044715f * x * x * x); const float e = fexp(2.f * z); const float th = 1.f - 2.f * __builtin_amdgcn_rcpf(e + 1.f); return 0.5f * x * (1.f + th); }
; __device__ __forceinline__ void wave_lds_fence() { asm volatile("s_waitcnt lgkmcnt(0)" ::: "memory"); }
; template <int PASS>
; __device__ __forceinline__ void s5_task(CArgs* Ap, int l, int b, int g, int c, LAS unsigned char* wl, int lane) {
;     ...
;         if (PASS == 2) {
;             wave_lds_fence();
;             f32x4 y = (f32x4){0.f, 0.f, 0.f, 0.f};
; #pragma unroll
;             for (int kk = 0; kk < 4; ++kk) { const bf16x8 xa = *(const LAS bf16x8*)(Xs + n16 * 136 + 32 * kk + 8 * g4); y = __builtin_amdgcn_mfma_f32_16x16x32_bf16(xa, cB[kk], y, 0, 0, 0); }
; #pragma unroll
;             for (int i = 0; i < 4; ++i) { const int tl = 4 * g4 + i; const float uv = us[tl * 16 + n16]; const float v = gelu_tanh(y[i] + dval * uv);
;                 Y1[(row0 + tb + tl) * DSSM + g * 16 + n16] = f2bf(v); }
;         }
;         wave_lds_fence();
.Ls52m_done:
	s_waitcnt lgkmcnt(0)
	ds_read_b128 v[16:19], v93 offset:1024
	ds_read_b128 v[28:31], v93 offset:1088
	ds_read_b128 v[98:101], v93 offset:1152
	v_or_b32_e32 v144, s16, v35
	v_lshl_add_u64 v[82:83], s[0:1], 0, v[144:145]
	s_waitcnt lgkmcnt(2)
	v_mfma_f32_16x16x32_bf16 v[16:19], v[16:19], v[0:3], 0
	v_or_b32_e32 v144, s16, v90
	s_and_b64 vcc, exec, s[14:15]
	s_waitcnt lgkmcnt(1)
	v_mfma_f32_16x16x32_bf16 v[28:31], v[28:31], v[4:7], v[16:19]
	s_nop 3
	ds_read_b128 v[16:19], v93 offset:1216
	s_waitcnt lgkmcnt(1)
	v_mfma_f32_16x16x32_bf16 v[28:31], v[98:101], v[8:11], v[28:31]
	ds_read_b32 v98, v94
	ds_read_b32 v99, v95
	ds_read_b32 v100, v96
	ds_read_b32 v101, v97
	s_waitcnt lgkmcnt(4)
	v_mfma_f32_16x16x32_bf16 v[16:19], v[16:19], v[12:15], v[28:31]
	s_waitcnt vmcnt(0) lgkmcnt(3)
	s_nop 6
	v_fma_f32 v28, v45, v98, v16
	v_mul_f32_e32 v16, 0x3d372713, v28
	v_mul_f32_e32 v16, v28, v16
	v_fma_f32 v16, v28, v16, v28
	v_mul_f32_e32 v16, 0x3f4c422a, v16
	v_add_f32_e32 v16, v16, v16
	v_mul_f32_e32 v16, 0x3fb8aa3b, v16
	v_exp_f32_e32 v30, v16
	s_waitcnt lgkmcnt(2)
	v_fma_f32 v29, v45, v99, v17
	v_mul_f32_e32 v17, 0x3d372713, v29
	v_mul_f32_e32 v17, v29, v17
	v_add_f32_e32 v30, 1.0, v30
	v_rcp_f32_e32 v30, v30
	v_fma_f32 v17, v29, v17, v29
	v_mul_f32_e32 v17, 0x3f4c422a, v17
	v_add_f32_e32 v17, v17, v17
	v_fma_f32 v30, v30, -2.0, 1.0
	v_mul_f32_e32 v17, 0x3fb8aa3b, v17
	v_mul_f32_e32 v28, 0.5, v28
	v_add_f32_e32 v30, 1.0, v30
	v_exp_f32_e32 v31, v17
	v_lshlrev_b64 v[16:17], 11, v[82:83]
	v_mul_f32_e32 v28, v28, v30
	v_lshl_add_u64 v[16:17], v[24:25], 0, v[16:17]
	v_cvt_pk_bf16_f32 v28, v28, s0
	s_waitcnt lgkmcnt(1)
	v_fma_f32 v18, v45, v100, v18
	global_store_short v[16:17], v28, off
	v_mul_f32_e32 v16, 0x3d372713, v18
	v_mul_f32_e32 v16, v18, v16
	v_fma_f32 v16, v18, v16, v18
	v_mul_f32_e32 v16, 0x3f4c422a, v16
	v_add_f32_e32 v16, v16, v16
	v_mul_f32_e32 v16, 0x3fb8aa3b, v16
	v_add_f32_e32 v31, 1.0, v31
	v_exp_f32_e32 v28, v16
	v_rcp_f32_e32 v31, v31
	v_mul_f32_e32 v29, 0.5, v29
	v_lshl_add_u64 v[16:17], s[0:1], 0, v[144:145]
	v_add_f32_e32 v28, 1.0, v28
	v_fma_f32 v31, v31, -2.0, 1.0
	v_rcp_f32_e32 v28, v28
	v_add_f32_e32 v31, 1.0, v31
	v_mul_f32_e32 v29, v29, v31
	v_lshlrev_b64 v[16:17], 11, v[16:17]
	v_cvt_pk_bf16_f32 v29, v29, s0
	v_lshl_add_u64 v[16:17], v[24:25], 0, v[16:17]
	global_store_short v[16:17], v29, off
	v_fma_f32 v16, v28, -2.0, 1.0
	v_mul_f32_e32 v17, 0.5, v18
	v_add_f32_e32 v16, 1.0, v16
	s_waitcnt lgkmcnt(0)
	v_fmac_f32_e32 v19, v45, v101
	v_mul_f32_e32 v16, v17, v16
	v_mul_f32_e32 v17, 0x3d372713, v19
	v_mul_f32_e32 v17, v19, v17
	v_fma_f32 v17, v19, v17, v19
	v_mul_f32_e32 v17, 0x3f4c422a, v17
	v_add_f32_e32 v17, v17, v17
	v_mul_f32_e32 v17, 0x3fb8aa3b, v17
	v_exp_f32_e32 v18, v17
	v_or_b32_e32 v144, s16, v91
	v_cvt_pk_bf16_f32 v28, v16, s0
	v_lshl_add_u64 v[16:17], s[0:1], 0, v[144:145]
	v_add_f32_e32 v18, 1.0, v18
	v_rcp_f32_e32 v18, v18
	v_lshlrev_b64 v[16:17], 11, v[16:17]
	v_lshl_add_u64 v[16:17], v[24:25], 0, v[16:17]
	global_store_short v[16:17], v28, off
	v_fma_f32 v16, v18, -2.0, 1.0
	v_mul_f32_e32 v17, 0.5, v19
	v_add_f32_e32 v16, 1.0, v16
	v_mul_f32_e32 v16, v17, v16
	v_or_b32_e32 v144, s16, v92
	v_cvt_pk_bf16_f32 v18, v16, s0
	v_lshl_add_u64 v[16:17], s[0:1], 0, v[144:145]
	v_lshlrev_b64 v[16:17], 11, v[16:17]
	v_lshl_add_u64 v[16:17], v[24:25], 0, v[16:17]
	global_store_short v[16:17], v18, off
	s_waitcnt lgkmcnt(0)
	v_mov_b64_e32 v[16:17], v[26:27]
	s_mov_b32 s16, s17
	s_cbranch_vccz .LBB0_879
	s_add_i32 s30, s30, s89
	s_add_i32 s28, s28, s29
	s_cmpk_gt_i32 s30, 0xff
	s_cbranch_scc0 .LBB0_868
